# P7: each workgroup touches its residual (x1b) tile with LDS-DMA dword loads at phase start so the epilogue's residual reads hit the memory-side cache
# baseline (speedup 1.0000x reference)
;     __device__ __forceinline__ long a_off(int pm, size_t tstep) const { return (long)pm * (long)tstep; }
; #define PG8_STAGE(bufoff, gbase, voff) do { _Pragma("unroll") for (int _i = 0; _i < 2; ++_i) \
;         __builtin_amdgcn_global_load_lds((const unsigned*)((const char*)(gbase) + (voff)[_i]), (PG8_LAS unsigned*)(lds + (bufoff) + ldsw + _i * 8192), 16, 0, 0); } while (0)
; #define PG8_WAIT_V(n) asm volatile("s_waitcnt vmcnt(" #n ")" ::: "memory")
; #define PG8_BAR __builtin_amdgcn_s_barrier()
; template <class Epi, class Sched, bool ALIGN_EPI = false, bool SP2 = false>
; __device__ __forceinline__ void gemm_phase(PG8_LAS unsigned char* lds, const Gemm g, const Sched& S, const Epi& E) {
;     ...
;     const char* cA = (const char*)g.A + S.a_off(cur.pm, tstep); const char* cB = (const char*)g.Bt + (size_t)cur.pn * tstep;
;     S.a_ready(cur);
;     if constexpr (SP2) {
;         PG8_STAGE(PG8_SB(0, 0), cB, voffB); PG8_STAGE(PG8_SB(0, 1), cB + hstep, voffB); PG8_STAGE(PG8_SA(0, 0), cA, voffA); PG8_STAGE(PG8_SA(0, 1), cA + hstep, voffA);
;         if (wr == 1) PG8_BAR;
;         PG8_WAIT_V(2); PG8_BAR;
;         PG8_STAGE(PG8_SB(1, 0), cB + kstep, voffB); PG8_STAGE(PG8_SA(1, 0), cA + kstep, voffA); PG8_STAGE(PG8_SB(1, 1), cB + hstep + kstep, voffB);
;         PG8_WAIT_V(6); PG8_BAR;
;     } else {
;         PG8_STAGE(PG8_SB(0, 0), cB, voffB); PG8_STAGE(PG8_SA(0, 0), cA, voffA); PG8_STAGE(PG8_SB(0, 1), cB + hstep, voffB); PG8_STAGE(PG8_SA(0, 1), cA + hstep, voffA);
;         if (wr == 1) PG8_BAR;
;         PG8_WAIT_V(4); PG8_BAR;
;         PG8_STAGE(PG8_SB(1, 0), cB + kstep, voffB); PG8_STAGE(PG8_SA(1, 0), cA + kstep, voffA); PG8_STAGE(PG8_SB(1, 1), cB + hstep + kstep, voffB);
;         PG8_WAIT_V(6); PG8_BAR;
;     __device__ __forceinline__ void operator()(const f32x4 (&acc)[2][2][4][2], const pg8::Unit& u, int wr, int wc, int fr, int fq) const {
;     ...
;             for (int m = 0; m < 4; ++m)
; #pragma unroll
;                 for (int bj = 0; bj < 2; ++bj) xw[m][bj] = __builtin_nontemporal_load((const u32x4*)(x1b + ((unsigned)(row0 + ai * 128 + m * 16) * D_ + colb + 128 * bj)));
.LBB0_658:
	s_add_u32 s27, s10, 0xa000000
	s_addc_u32 s30, s11, 0
	s_add_u32 s31, s10, 0x1900000
	s_addc_u32 s33, s11, 0
	s_add_i32 s1, s6, s1
	s_ashr_i32 s6, s1, 31
	s_lshr_b32 s6, s6, 27
	s_add_i32 s6, s1, s6
	s_ashr_i32 s7, s6, 5
	s_and_b32 s6, s6, 0xffe0
	v_lshlrev_b32_e32 v1, 4, v0
	v_and_b32_e32 v2, 32, v208
	s_sub_i32 s6, s1, s6
	v_bitop3_b32 v8, v1, v2, 48 bitop3:0x6c
	v_lshrrev_b32_e32 v2, 1, v208
	s_bfe_i32 s1, s6, 0x80000
	v_and_b32_e32 v10, 24, v2
	v_lshrrev_b32_e32 v2, 5, v208
	s_bfe_u32 s1, s1, 0x3000c
	v_and_b32_e32 v2, 4, v2
	v_bfe_u32 v4, v208, 2, 2
	s_add_i32 s12, s6, s1
	v_bfe_u32 v3, v208, 2, 4
	v_or3_b32 v2, v2, v4, v10
	v_lshrrev_b32_e32 v0, 3, v0
	s_bfe_i32 s1, s12, 0x80000
	s_and_b32 s12, s12, 0xf8
	v_and_b32_e32 v9, 64, v208
	v_and_or_b32 v4, v0, 48, v3
	v_and_or_b32 v5, v0, 32, v2
	v_or_b32_e32 v0, 64, v0
	s_movk_i32 s5, 0x70
	s_sub_i32 s6, s6, s12
	v_or_b32_e32 v1, v8, v9
	v_and_or_b32 v3, v0, s5, v3
	s_movk_i32 s5, 0x60
	s_lshl_b32 s7, s7, 3
	s_sext_i32_i16 s13, s1
	s_sext_i32_i8 s6, s6
	v_lshrrev_b32_e32 v1, 1, v1
	v_mul_u32_u24_e32 v11, 0xb00, v4
	v_and_or_b32 v0, v0, s5, v2
	s_lshr_b32 s5, s4, 6
	s_add_i32 s48, s7, s6
	s_ashr_i32 s6, s13, 3
	s_lshr_b32 s0, s4, 8
	v_or_b32_e32 v4, v1, v11
	s_lshl_b32 s34, s5, 10
	s_lshr_b32 s1, s13, 3
	s_mul_hi_i32 s7, s6, 0x160000
	s_mul_i32 s6, s6, 0x160000
	v_lshlrev_b32_e32 v144, 1, v4
	v_mul_u32_u24_e32 v4, 0xb00, v5
	s_add_u32 s24, s31, s6
	v_or_b32_e32 v4, v4, v1
	s_addc_u32 s25, s33, s7
	s_add_i32 s35, s34, 0
	v_lshlrev_b32_e32 v146, 1, v4
	v_mul_u32_u24_e32 v0, 0xb00, v0
	s_add_i32 m0, s35, 0x10000
	v_or_b32_e32 v0, v0, v1
	global_load_lds_dwordx4 v146, s[24:25]
	s_add_i32 m0, s35, 0x12000
	v_lshlrev_b32_e32 v150, 1, v0
	s_add_u32 s6, s24, 0xb0000
	global_load_lds_dwordx4 v150, s[24:25]
	s_addc_u32 s7, s25, 0
	s_add_i32 m0, s35, 0x14000
	s_mul_i32 s14, s48, 0x160000
	global_load_lds_dwordx4 v146, s[6:7]
	s_add_i32 m0, s35, 0x16000
	s_mul_hi_i32 s12, s48, 0x160000
	s_add_u32 s22, s27, s14
	v_mul_u32_u24_e32 v12, 0xb00, v3
	s_addc_u32 s23, s30, s12
	s_add_i32 s36, s35, 0x2000
	v_or_b32_e32 v2, v12, v1
	global_load_lds_dwordx4 v150, s[6:7]
	s_mov_b32 m0, s35
	s_add_u32 s6, s22, 0xb0000
	v_lshlrev_b32_e32 v148, 1, v2
	global_load_lds_dwordx4 v144, s[22:23]
	s_mov_b32 m0, s36
	s_addc_u32 s7, s23, 0
	s_add_i32 s37, s35, 0x4000
	global_load_lds_dwordx4 v148, s[22:23]
	s_mov_b32 m0, s37
	s_add_i32 s38, s35, 0x6000
	global_load_lds_dwordx4 v144, s[6:7]
	s_mov_b32 m0, s38
	v_mov_b32_e32 v153, 0
	global_load_lds_dwordx4 v148, s[6:7]
	v_and_b32_e32 v16, 0x1ff, v208
	v_lshrrev_b32_e32 v17, 1, v16
	v_and_b32_e32 v16, 1, v16
	v_lshlrev_b32_e32 v17, 11, v17
	v_lshl_or_b32 v16, v16, 8, v17
	s_ashr_i32 s74, s13, 3
	s_lshl_b32 s74, s74, 9
	s_lshl_b32 s75, s48, 19
	s_add_i32 s74, s74, s75
	s_add_u32 s76, s10, 0x4000000
	s_addc_u32 s77, s11, 0
	s_add_u32 s76, s76, s74
	s_addc_u32 s77, s77, 0
	s_mov_b32 m0, 0x20040
	s_nop 0
	global_load_lds_dword v16, s[76:77]
	global_load_lds_dword v16, s[76:77] offset:128
	v_mov_b32_e32 v147, v153
	v_mov_b32_e32 v151, v153
	v_mov_b32_e32 v145, v153
	v_mov_b32_e32 v149, v153
	s_cmp_eq_u32 s0, 1
	s_mov_b32 s39, 0
	v_lshl_add_u64 v[6:7], s[24:25], 0, v[146:147]
	v_lshl_add_u64 v[4:5], s[24:25], 0, v[150:151]
	v_lshl_add_u64 v[0:1], s[22:23], 0, v[144:145]
	s_cselect_b64 s[6:7], -1, 0
	s_cmp_lg_u32 s0, 1
	v_lshl_add_u64 v[2:3], s[22:23], 0, v[148:149]
	s_cbranch_scc1 .LBB0_660
	s_barrier
.LBB0_660:
	s_add_u32 s12, s10, 0x4000000
	s_addc_u32 s13, s11, 0
	s_lshl_b32 s5, s5, 5
	s_mov_b64 s[14:15], 0x80
	s_and_b32 s5, s5, 0x60
	s_add_i32 m0, s35, 0x18000
	v_lshl_add_u64 v[6:7], v[6:7], 0, s[14:15]
	s_lshl_b32 s18, s0, 13
	s_lshl_b32 s19, s5, 7
	s_waitcnt vmcnt(4)
	s_barrier
	global_load_lds_dwordx4 v[6:7], off
	v_lshl_add_u64 v[4:5], v[4:5], 0, s[14:15]
	s_add_i32 m0, s35, 0x1a000
	s_add_i32 s40, s35, 0x8000
	s_add_i32 s41, s35, 0xa000
	global_load_lds_dwordx4 v[4:5], off
	v_lshl_add_u64 v[0:1], v[0:1], 0, s[14:15]
	s_mov_b32 m0, s40
	s_add_u32 s16, s24, 0xb0080
	global_load_lds_dwordx4 v[0:1], off
	v_lshl_add_u64 v[0:1], v[2:3], 0, s[14:15]
	s_mov_b32 m0, s41
	s_addc_u32 s17, s25, 0
	global_load_lds_dwordx4 v[0:1], off
	s_add_i32 m0, s35, 0x1c000
	v_lshl_add_u64 v[0:1], s[16:17], 0, v[146:147]
	global_load_lds_dwordx4 v[0:1], off
	v_lshl_add_u64 v[0:1], s[16:17], 0, v[150:151]
	s_add_i32 m0, s35, 0x1e000
	v_lshlrev_b32_e32 v2, 2, v208
	global_load_lds_dwordx4 v[0:1], off
	v_and_b32_e32 v0, 15, v208
	v_lshlrev_b32_e32 v1, 1, v10
	v_lshl_or_b32 v1, v0, 6, v1
	v_lshlrev_b32_e32 v0, 10, v0
	v_and_b32_e32 v2, 32, v2
	s_waitcnt vmcnt(8)
	s_cmpk_lt_u32 s4, 0x100
	v_lshl_or_b32 v169, s0, 16, v0
	v_add_u16_e32 v0, v8, v9
	v_bitop3_b32 v3, v1, s18, v2 bitop3:0xde
	v_bitop3_b32 v168, v1, s19, v2 bitop3:0xde
	s_cselect_b64 s[16:17], -1, 0
	v_lshrrev_b16_e32 v0, 1, v0
	s_add_i32 s43, 0, 0x10000
	s_add_i32 s44, 0, 0x14000
	s_sext_i32_i8 s49, s1
	s_ashr_i32 s42, s26, 31
	v_or_b32_e32 v170, s5, v10
	v_add_lshl_u32 v154, v11, v0, 1
	v_mov_b32_e32 v155, v153
	v_add_lshl_u32 v156, v12, v0, 1
	v_mov_b32_e32 v157, v153
	v_mov_b64_e32 v[158:159], 0x100
	v_mov_b64_e32 v[160:161], 0xff
	v_add_u32_e32 v171, s43, v168
	v_add_u32_e32 v172, s44, v168
	v_add_u32_e32 v173, 0, v3
	s_mov_b64 s[18:19], 0x5000
	s_movk_i32 s45, 0x5000
	s_barrier
	s_branch .LBB0_663
